# grid barrier: XCD-last bumps its XCD generation word (no-return atomic), all blocks poll the 8 per-XCD words; no top-level returned atomic
# speedup vs baseline: 1.0068x; 1.0068x over previous
.LBB0_218:
	s_or_b64 exec, exec, s[2:3]
	v_cvt_f32_u32_e32 v4, v2
	s_waitcnt vmcnt(0)
	v_readfirstlane_b32 s2, v3
	v_sub_u32_e32 v3, 0, v2
	v_rcp_iflag_f32_e32 v4, v4
	v_add_u32_e32 v5, s2, v1
	v_mul_f32_e32 v4, 0x4f7ffffe, v4
	v_cvt_u32_f32_e32 v4, v4
	v_mul_lo_u32 v1, v3, v4
	v_mul_hi_u32 v1, v4, v1
	v_add_u32_e32 v1, v4, v1
	v_mul_hi_u32 v1, v5, v1
	v_mul_lo_u32 v3, v1, v2
	v_sub_u32_e32 v3, v5, v3
	v_add_u32_e32 v4, 1, v1
	v_cmp_ge_u32_e32 vcc, v3, v2
	s_nop 1
	v_cndmask_b32_e32 v1, v1, v4, vcc
	v_sub_u32_e32 v4, v3, v2
	v_cndmask_b32_e32 v3, v3, v4, vcc
	v_add_u32_e32 v4, 1, v1
	v_cmp_ge_u32_e32 vcc, v3, v2
	v_add_u32_e32 v3, 1, v5
	s_nop 0
	v_cndmask_b32_e32 v1, v1, v4, vcc
	v_mul_lo_u32 v4, v2, v1
	v_add_u32_e32 v2, v4, v2
	v_cmp_ne_u32_e32 vcc, v3, v2
	s_cbranch_vccnz .Lgs1_poll
	buffer_wbl2 sc1
	s_waitcnt vmcnt(0) lgkmcnt(0)
	v_mov_b32_e32 v10, 0
	v_mov_b32_e32 v11, 1
	v_readlane_b32 s6, v236, 32
	v_readlane_b32 s7, v236, 33
	s_nop 4
	global_atomic_add v10, v11, s[6:7]
.Lgs1_poll:
	s_mov_b64 vcc, exec
	s_and_saveexec_b64 s[2:3], vcc
	s_xor_b64 s[2:3], exec, s[2:3]
	s_cbranch_execz .LBB0_232
	s_add_u32 s6, s24, 0x2400
	s_waitcnt lgkmcnt(0)
	v_mov_b32_e32 v0, 0
	s_addc_u32 s7, s25, 0
	s_nop 4
	global_load_dword v10, v0, s[6:7] sc1
	global_load_dword v11, v0, s[6:7] offset:256 sc1
	global_load_dword v12, v0, s[6:7] offset:512 sc1
	global_load_dword v13, v0, s[6:7] offset:768 sc1
	global_load_dword v14, v0, s[6:7] offset:1024 sc1
	global_load_dword v15, v0, s[6:7] offset:1280 sc1
	global_load_dword v16, v0, s[6:7] offset:1536 sc1
	global_load_dword v17, v0, s[6:7] offset:1792 sc1
	s_waitcnt vmcnt(0)
	v_add3_u32 v10, v10, v11, v12
	v_add3_u32 v13, v13, v14, v15
	v_add3_u32 v10, v10, v13, v16
	v_add_u32_e32 v2, v10, v17
	v_lshrrev_b32_e32 v2, 3, v2
	v_cmp_eq_u32_e32 vcc, v2, v1
	s_and_saveexec_b64 s[6:7], vcc
	s_cbranch_execz .LBB0_231
	s_mov_b32 s19, 1
	s_mov_b64 s[8:9], 0
	s_branch .LBB0_222

.LBB0_226:
	s_add_u32 s12, s24, 0x2400
	s_addc_u32 s13, s25, 0
	s_add_i32 s19, s19, 1
	s_mov_b64 s[14:15], -1
	s_nop 2
	global_load_dword v10, v0, s[12:13] sc1
	global_load_dword v11, v0, s[12:13] offset:256 sc1
	global_load_dword v12, v0, s[12:13] offset:512 sc1
	global_load_dword v13, v0, s[12:13] offset:768 sc1
	global_load_dword v14, v0, s[12:13] offset:1024 sc1
	global_load_dword v15, v0, s[12:13] offset:1280 sc1
	global_load_dword v16, v0, s[12:13] offset:1536 sc1
	global_load_dword v17, v0, s[12:13] offset:1792 sc1
	s_waitcnt vmcnt(0)
	v_add3_u32 v10, v10, v11, v12
	v_add3_u32 v13, v13, v14, v15
	v_add3_u32 v10, v10, v13, v16
	v_add_u32_e32 v2, v10, v17
	v_lshrrev_b32_e32 v2, 3, v2
	v_cmp_ne_u32_e32 vcc, v2, v1
	s_orn2_b64 s[12:13], vcc, exec
	s_branch .LBB0_221

.LBB0_292:
	s_or_b64 exec, exec, s[12:13]
	v_cvt_f32_u32_e32 v5, v2
	s_waitcnt vmcnt(0)
	v_readfirstlane_b32 s12, v4
	v_sub_u32_e32 v4, 0, v2
	v_rcp_iflag_f32_e32 v5, v5
	v_add_u32_e32 v6, s12, v1
	v_mul_f32_e32 v5, 0x4f7ffffe, v5
	v_cvt_u32_f32_e32 v5, v5
	v_mul_lo_u32 v1, v4, v5
	v_mul_hi_u32 v1, v5, v1
	v_add_u32_e32 v1, v5, v1
	v_mul_hi_u32 v1, v6, v1
	v_mul_lo_u32 v4, v1, v2
	v_sub_u32_e32 v4, v6, v4
	v_add_u32_e32 v5, 1, v1
	v_cmp_ge_u32_e32 vcc, v4, v2
	s_nop 1
	v_cndmask_b32_e32 v1, v1, v5, vcc
	v_sub_u32_e32 v5, v4, v2
	v_cndmask_b32_e32 v4, v4, v5, vcc
	v_add_u32_e32 v5, 1, v1
	v_cmp_ge_u32_e32 vcc, v4, v2
	v_add_u32_e32 v4, 1, v6
	s_nop 0
	v_cndmask_b32_e32 v1, v1, v5, vcc
	v_mul_lo_u32 v5, v2, v1
	v_add_u32_e32 v2, v5, v2
	v_cmp_ne_u32_e32 vcc, v4, v2
	s_cbranch_vccnz .Lgs2_poll
	buffer_wbl2 sc1
	s_waitcnt vmcnt(0) lgkmcnt(0)
	v_mov_b32_e32 v10, 0
	v_mov_b32_e32 v11, 1
	v_readlane_b32 s40, v236, 32
	v_readlane_b32 s41, v236, 33
	s_nop 4
	global_atomic_add v10, v11, s[40:41]
.Lgs2_poll:
	s_mov_b64 vcc, exec
	s_and_saveexec_b64 s[12:13], vcc
	s_xor_b64 s[12:13], exec, s[12:13]
	s_cbranch_execz .LBB0_306
	s_add_u32 s40, s24, 0x2400
	s_addc_u32 s41, s25, 0
	s_waitcnt lgkmcnt(0)
	s_nop 3
	global_load_dword v10, v3, s[40:41] sc1
	global_load_dword v11, v3, s[40:41] offset:256 sc1
	global_load_dword v12, v3, s[40:41] offset:512 sc1
	global_load_dword v13, v3, s[40:41] offset:768 sc1
	global_load_dword v14, v3, s[40:41] offset:1024 sc1
	global_load_dword v15, v3, s[40:41] offset:1280 sc1
	global_load_dword v16, v3, s[40:41] offset:1536 sc1
	global_load_dword v17, v3, s[40:41] offset:1792 sc1
	s_waitcnt vmcnt(0)
	v_add3_u32 v10, v10, v11, v12
	v_add3_u32 v13, v13, v14, v15
	v_add3_u32 v10, v10, v13, v16
	v_add_u32_e32 v0, v10, v17
	v_lshrrev_b32_e32 v0, 3, v0
	v_cmp_eq_u32_e32 vcc, v0, v1
	s_and_saveexec_b64 s[40:41], vcc
	s_cbranch_execz .LBB0_305
	s_mov_b32 s15, 1
	s_mov_b64 s[42:43], 0
	s_branch .LBB0_296

.LBB0_300:
	s_add_u32 s46, s24, 0x2400
	s_addc_u32 s47, s25, 0
	s_add_i32 s15, s15, 1
	s_mov_b64 s[48:49], -1
	s_nop 2
	global_load_dword v10, v3, s[46:47] sc1
	global_load_dword v11, v3, s[46:47] offset:256 sc1
	global_load_dword v12, v3, s[46:47] offset:512 sc1
	global_load_dword v13, v3, s[46:47] offset:768 sc1
	global_load_dword v14, v3, s[46:47] offset:1024 sc1
	global_load_dword v15, v3, s[46:47] offset:1280 sc1
	global_load_dword v16, v3, s[46:47] offset:1536 sc1
	global_load_dword v17, v3, s[46:47] offset:1792 sc1
	s_waitcnt vmcnt(0)
	v_add3_u32 v10, v10, v11, v12
	v_add3_u32 v13, v13, v14, v15
	v_add3_u32 v10, v10, v13, v16
	v_add_u32_e32 v0, v10, v17
	v_lshrrev_b32_e32 v0, 3, v0
	v_cmp_ne_u32_e32 vcc, v0, v1
	s_orn2_b64 s[46:47], vcc, exec
	s_branch .LBB0_295

.Lgs3_poll:
	s_mov_b64 vcc, exec
	s_and_saveexec_b64 s[12:13], vcc
	s_xor_b64 s[12:13], exec, s[12:13]
	s_cbranch_execz .LBB0_513
	s_add_u32 s40, s24, 0x2400
	s_addc_u32 s41, s25, 0
	s_waitcnt lgkmcnt(0)
	s_nop 3
	global_load_dword v10, v3, s[40:41] sc1
	global_load_dword v11, v3, s[40:41] offset:256 sc1
	global_load_dword v12, v3, s[40:41] offset:512 sc1
	global_load_dword v13, v3, s[40:41] offset:768 sc1
	global_load_dword v14, v3, s[40:41] offset:1024 sc1
	global_load_dword v15, v3, s[40:41] offset:1280 sc1
	global_load_dword v16, v3, s[40:41] offset:1536 sc1
	global_load_dword v17, v3, s[40:41] offset:1792 sc1
	s_waitcnt vmcnt(0)
	v_add3_u32 v10, v10, v11, v12
	v_add3_u32 v13, v13, v14, v15
	v_add3_u32 v10, v10, v13, v16
	v_add_u32_e32 v0, v10, v17
	v_lshrrev_b32_e32 v0, 3, v0
	v_cmp_eq_u32_e32 vcc, v0, v1
	s_and_saveexec_b64 s[40:41], vcc
	s_cbranch_execz .LBB0_512
	s_mov_b32 s34, 1
	s_mov_b64 s[42:43], 0
	s_branch .LBB0_503

.LBB0_507:
	s_add_u32 s46, s24, 0x2400
	s_addc_u32 s47, s25, 0
	s_add_i32 s34, s34, 1
	s_mov_b64 s[48:49], -1
	s_nop 2
	global_load_dword v10, v3, s[46:47] sc1
	global_load_dword v11, v3, s[46:47] offset:256 sc1
	global_load_dword v12, v3, s[46:47] offset:512 sc1
	global_load_dword v13, v3, s[46:47] offset:768 sc1
	global_load_dword v14, v3, s[46:47] offset:1024 sc1
	global_load_dword v15, v3, s[46:47] offset:1280 sc1
	global_load_dword v16, v3, s[46:47] offset:1536 sc1
	global_load_dword v17, v3, s[46:47] offset:1792 sc1
	s_waitcnt vmcnt(0)
	v_add3_u32 v10, v10, v11, v12
	v_add3_u32 v13, v13, v14, v15
	v_add3_u32 v10, v10, v13, v16
	v_add_u32_e32 v0, v10, v17
	v_lshrrev_b32_e32 v0, 3, v0
	v_cmp_ne_u32_e32 vcc, v0, v1
	s_orn2_b64 s[46:47], vcc, exec
	s_branch .LBB0_502

.LBB0_1081:
	s_or_b64 exec, exec, s[2:3]
	v_cvt_f32_u32_e32 v4, v2
	s_waitcnt vmcnt(0)
	v_readfirstlane_b32 s2, v3
	v_sub_u32_e32 v3, 0, v2
	v_rcp_iflag_f32_e32 v4, v4
	v_add_u32_e32 v5, s2, v1
	v_mul_f32_e32 v4, 0x4f7ffffe, v4
	v_cvt_u32_f32_e32 v4, v4
	v_mul_lo_u32 v1, v3, v4
	v_mul_hi_u32 v1, v4, v1
	v_add_u32_e32 v1, v4, v1
	v_mul_hi_u32 v1, v5, v1
	v_mul_lo_u32 v3, v1, v2
	v_sub_u32_e32 v3, v5, v3
	v_add_u32_e32 v4, 1, v1
	v_cmp_ge_u32_e32 vcc, v3, v2
	s_nop 1
	v_cndmask_b32_e32 v1, v1, v4, vcc
	v_sub_u32_e32 v4, v3, v2
	v_cndmask_b32_e32 v3, v3, v4, vcc
	v_add_u32_e32 v4, 1, v1
	v_cmp_ge_u32_e32 vcc, v3, v2
	v_add_u32_e32 v3, 1, v5
	s_nop 0
	v_cndmask_b32_e32 v1, v1, v4, vcc
	v_mul_lo_u32 v4, v2, v1
	v_add_u32_e32 v2, v4, v2
	v_cmp_ne_u32_e32 vcc, v3, v2
	s_cbranch_vccnz .Lgs7_poll
	buffer_wbl2 sc1
	s_waitcnt vmcnt(0) lgkmcnt(0)
	v_mov_b32_e32 v10, 0
	v_mov_b32_e32 v11, 1
	v_readlane_b32 s4, v236, 32
	v_readlane_b32 s5, v236, 33
	s_nop 4
	global_atomic_add v10, v11, s[4:5]
.Lgs7_poll:
	s_mov_b64 vcc, exec
	s_and_saveexec_b64 s[2:3], vcc
	s_xor_b64 s[2:3], exec, s[2:3]
	s_cbranch_execz .LBB0_1095
	s_add_u32 s4, s24, 0x2400
	s_waitcnt lgkmcnt(0)
	v_mov_b32_e32 v0, 0
	s_addc_u32 s5, s25, 0
	s_nop 4
	global_load_dword v10, v0, s[4:5] sc1
	global_load_dword v11, v0, s[4:5] offset:256 sc1
	global_load_dword v12, v0, s[4:5] offset:512 sc1
	global_load_dword v13, v0, s[4:5] offset:768 sc1
	global_load_dword v14, v0, s[4:5] offset:1024 sc1
	global_load_dword v15, v0, s[4:5] offset:1280 sc1
	global_load_dword v16, v0, s[4:5] offset:1536 sc1
	global_load_dword v17, v0, s[4:5] offset:1792 sc1
	s_waitcnt vmcnt(0)
	v_add3_u32 v10, v10, v11, v12
	v_add3_u32 v13, v13, v14, v15
	v_add3_u32 v10, v10, v13, v16
	v_add_u32_e32 v2, v10, v17
	v_lshrrev_b32_e32 v2, 3, v2
	v_cmp_eq_u32_e32 vcc, v2, v1
	s_and_saveexec_b64 s[4:5], vcc
	s_cbranch_execz .LBB0_1094
	s_mov_b32 s16, 1
	s_mov_b64 s[6:7], 0
	s_branch .LBB0_1085

.LBB0_1089:
	s_add_u32 s10, s24, 0x2400
	s_addc_u32 s11, s25, 0
	s_add_i32 s16, s16, 1
	s_mov_b64 s[12:13], -1
	s_nop 2
	global_load_dword v10, v0, s[10:11] sc1
	global_load_dword v11, v0, s[10:11] offset:256 sc1
	global_load_dword v12, v0, s[10:11] offset:512 sc1
	global_load_dword v13, v0, s[10:11] offset:768 sc1
	global_load_dword v14, v0, s[10:11] offset:1024 sc1
	global_load_dword v15, v0, s[10:11] offset:1280 sc1
	global_load_dword v16, v0, s[10:11] offset:1536 sc1
	global_load_dword v17, v0, s[10:11] offset:1792 sc1
	s_waitcnt vmcnt(0)
	v_add3_u32 v10, v10, v11, v12
	v_add3_u32 v13, v13, v14, v15
	v_add3_u32 v10, v10, v13, v16
	v_add_u32_e32 v2, v10, v17
	v_lshrrev_b32_e32 v2, 3, v2
	v_cmp_ne_u32_e32 vcc, v2, v1
	s_orn2_b64 s[10:11], vcc, exec
	s_branch .LBB0_1084
